# baseline (speedup 1.0000x reference)
; #define LAS __attribute__((address_space(3)))
; DI int ltid() { int x = threadIdx.x; asm volatile("" : "+v"(x)); return x; }
; __global__ void __launch_bounds__(256, 2) trunk_fwd(Params p) {
;   __shared__ __attribute__((aligned(1024))) char smem[SM_TOTAL];
;   if (ltid() < 4) ((unsigned*)(smem + SM_BAR))[ltid()] = 0u;
;   __syncthreads();
;   XcdBarrier xb = xcd_barrier_post(p.bar, (volatile LAS unsigned*)(smem + SM_BAR));
;   const int plo = (int)p.phase_lo, phi = (int)p.phase_hi;
_Z9trunk_fwd6Params:
	v_and_b32_e32 v222, 0x3ff, v0
	v_mov_b32_e32 v1, v222
	s_mov_b32 s43, s2
	s_cmpk_ge_u32 s2, 0x100
	s_cbranch_scc1 .Lprio_done
	s_setprio 1
